# O_PMIX row loop: the four per-row reloads of the gain vector issued together with the row loads (hoisted above stores that cannot alias them)
# speedup vs baseline: 1.0005x; 1.0005x over previous
.LBB0_463:
	v_add_u32_e32 v56, s2, v70
	v_ashrrev_i32_e32 v57, 31, v56
	v_lshlrev_b64 v[2:3], 11, v[56:57]
	v_lshl_add_u64 v[2:3], s[62:63], 0, v[2:3]
	v_lshl_add_u64 v[2:3], v[2:3], 0, v[0:1]
	global_load_dwordx4 v[34:37], v[2:3], off
	v_add_co_u32_e32 v2, vcc, 0x1400000, v2
	v_mov_b64_e32 v[10:11], s[74:75]
	s_nop 0
	v_addc_co_u32_e32 v3, vcc, 0, v3, vcc
	global_load_dwordx4 v[38:41], v[2:3], off
	v_mad_i64_i32 v[2:3], s[2:3], v56, s85, v[10:11]
	v_lshl_add_u64 v[2:3], v[2:3], 0, v[0:1]
	v_add_co_u32_e32 v2, vcc, s4, v2
	v_add_u32_e32 v54, 32, v56
	s_nop 0
	v_addc_co_u32_e32 v3, vcc, 0, v3, vcc
	global_load_dwordx4 v[58:61], v[2:3], off offset:2048
	v_ashrrev_i32_e32 v55, 31, v54
	v_lshlrev_b64 v[2:3], 11, v[54:55]
	v_lshl_add_u64 v[2:3], s[62:63], 0, v[2:3]
	v_lshl_add_u64 v[2:3], v[2:3], 0, v[0:1]
	global_load_dwordx4 v[26:29], v[2:3], off
	v_add_co_u32_e32 v2, vcc, s5, v2
	v_add_u32_e32 v52, 64, v56
	s_nop 0
	v_addc_co_u32_e32 v3, vcc, 0, v3, vcc
	global_load_dwordx4 v[30:33], v[2:3], off
	v_mad_i64_i32 v[2:3], s[2:3], v54, s85, v[10:11]
	v_lshl_add_u64 v[2:3], v[2:3], 0, v[0:1]
	v_add_co_u32_e32 v2, vcc, s4, v2
	v_ashrrev_i32_e32 v53, 31, v52
	s_nop 0
	v_addc_co_u32_e32 v3, vcc, 0, v3, vcc
	global_load_dwordx4 v[42:45], v[2:3], off offset:2048
	v_lshlrev_b64 v[2:3], 11, v[52:53]
	v_lshl_add_u64 v[2:3], s[62:63], 0, v[2:3]
	v_lshl_add_u64 v[2:3], v[2:3], 0, v[0:1]
	global_load_dwordx4 v[14:17], v[2:3], off
	v_add_co_u32_e32 v2, vcc, s5, v2
	v_add_u32_e32 v50, 0x60, v56
	s_nop 0
	v_addc_co_u32_e32 v3, vcc, 0, v3, vcc
	global_load_dwordx4 v[18:21], v[2:3], off
	v_mad_i64_i32 v[2:3], s[2:3], v52, s85, v[10:11]
	v_lshl_add_u64 v[2:3], v[2:3], 0, v[0:1]
	v_add_co_u32_e32 v2, vcc, s4, v2
	v_ashrrev_i32_e32 v51, 31, v50
	s_nop 0
	v_addc_co_u32_e32 v3, vcc, 0, v3, vcc
	global_load_dwordx4 v[22:25], v[2:3], off offset:2048
	v_lshlrev_b64 v[2:3], 11, v[50:51]
	v_lshl_add_u64 v[2:3], s[62:63], 0, v[2:3]
	v_lshl_add_u64 v[6:7], v[2:3], 0, v[0:1]
	global_load_dwordx4 v[2:5], v[6:7], off
	v_add_co_u32_e32 v6, vcc, s5, v6
	v_mad_i64_i32 v[10:11], s[2:3], v50, s85, v[10:11]
	s_nop 0
	v_addc_co_u32_e32 v7, vcc, 0, v7, vcc
	global_load_dwordx4 v[6:9], v[6:7], off
	v_lshl_add_u64 v[10:11], v[10:11], 0, v[0:1]
	v_add_co_u32_e32 v10, vcc, s4, v10
	s_nop 0
	s_nop 0
	v_addc_co_u32_e32 v11, vcc, 0, v11, vcc
	global_load_dwordx4 v[10:13], v[10:11], off offset:2048
	s_movk_i32 s2, 0x80
	s_and_b64 vcc, exec, s[0:1]
	global_load_dwordx4 v[88:91], v[48:49], off offset:16
	global_load_dwordx4 v[76:79], v[48:49], off
	global_load_dwordx4 v[92:95], v[48:49], off offset:16
	global_load_dwordx4 v[132:135], v[48:49], off
	global_load_dwordx4 v[136:139], v[48:49], off offset:16
	global_load_dwordx4 v[140:143], v[48:49], off
	global_load_dwordx4 v[144:147], v[48:49], off offset:16
	global_load_dwordx4 v[148:151], v[48:49], off
	s_mov_b64 s[0:1], 0
	s_waitcnt vmcnt(20)
	s_waitcnt vmcnt(19)
	v_lshlrev_b32_e32 v72, 16, v36
	v_and_b32_e32 v73, 0xffff0000, v36
	v_lshlrev_b32_e32 v80, 16, v35
	v_and_b32_e32 v81, 0xffff0000, v35
	v_lshlrev_b32_e32 v84, 16, v34
	v_and_b32_e32 v85, 0xffff0000, v34
	s_waitcnt vmcnt(18)
	v_lshlrev_b32_e32 v36, 16, v40
	v_lshlrev_b32_e32 v34, 16, v38
	v_and_b32_e32 v35, 0xffff0000, v38
	v_lshlrev_b32_e32 v82, 16, v39
	v_and_b32_e32 v83, 0xffff0000, v39
	v_pk_add_f32 v[34:35], v[84:85], v[34:35]
	v_pk_add_f32 v[80:81], v[80:81], v[82:83]
	v_pk_mul_f32 v[38:39], v[34:35], v[34:35]
	v_pk_mul_f32 v[82:83], v[80:81], v[80:81]
	s_waitcnt vmcnt(17)
	v_lshlrev_b32_e32 v62, 16, v58
	v_and_b32_e32 v63, 0xffff0000, v58
	v_lshlrev_b32_e32 v66, 16, v60
	v_and_b32_e32 v67, 0xffff0000, v60
	v_lshlrev_b32_e32 v64, 16, v59
	v_and_b32_e32 v65, 0xffff0000, v59
	v_mul_f32_e32 v58, 0xbfb8aa3b, v62
	v_mul_f32_e32 v59, 0xbfb8aa3b, v63
	v_mul_f32_e32 v62, 0xbfb8aa3b, v66
	v_mul_f32_e32 v63, 0xbfb8aa3b, v67
	v_lshlrev_b32_e32 v66, 16, v37
	v_and_b32_e32 v67, 0xffff0000, v37
	v_and_b32_e32 v37, 0xffff0000, v40
	v_pk_add_f32 v[36:37], v[72:73], v[36:37]
	s_nop 0
	s_nop 0
	v_add_f32_e32 v38, v38, v39
	v_lshlrev_b32_e32 v68, 16, v61
	v_and_b32_e32 v69, 0xffff0000, v61
	v_add_f32_e32 v38, v82, v38
	v_mul_f32_e32 v60, 0xbfb8aa3b, v64
	v_mul_f32_e32 v61, 0xbfb8aa3b, v65
	v_mul_f32_e32 v64, 0xbfb8aa3b, v68
	v_mul_f32_e32 v65, 0xbfb8aa3b, v69
	v_lshlrev_b32_e32 v68, 16, v41
	v_and_b32_e32 v69, 0xffff0000, v41
	v_pk_mul_f32 v[40:41], v[36:37], v[36:37]
	v_add_f32_e32 v38, v83, v38
	v_pk_add_f32 v[66:67], v[66:67], v[68:69]
	v_add_f32_e32 v38, v40, v38
	v_pk_mul_f32 v[68:69], v[66:67], v[66:67]
	v_add_f32_e32 v38, v41, v38
	v_add_f32_e32 v38, v68, v38
	v_add_f32_e32 v38, v69, v38
	v_exp_f32_e32 v62, v62
	v_exp_f32_e32 v63, v63
	v_add_f32_dpp v38, v38, v38 quad_perm:[1,0,3,2] row_mask:0xf bank_mask:0xf bound_ctrl:1
	v_exp_f32_e32 v64, v64
	v_exp_f32_e32 v65, v65
	v_add_f32_dpp v38, v38, v38 quad_perm:[2,3,0,1] row_mask:0xf bank_mask:0xf bound_ctrl:1
	v_exp_f32_e32 v58, v58
	v_exp_f32_e32 v59, v59
	v_add_f32_dpp v38, v38, v38 row_half_mirror row_mask:0xf bank_mask:0xf bound_ctrl:1
	v_exp_f32_e32 v60, v60
	v_exp_f32_e32 v61, v61
	v_add_f32_dpp v38, v38, v38 row_mirror row_mask:0xf bank_mask:0xf bound_ctrl:1
	v_fmamk_f32 v38, v38, 0x3c000000, v233
	v_rsq_f32_e32 v38, v38
	v_add_f32_e32 v62, 1.0, v62
	v_add_f32_e32 v63, 1.0, v63
	v_add_f32_e32 v64, 1.0, v64
	v_add_f32_e32 v65, 1.0, v65
	v_add_f32_e32 v58, 1.0, v58
	v_add_f32_e32 v59, 1.0, v59
	v_add_f32_e32 v60, 1.0, v60
	v_add_f32_e32 v61, 1.0, v61
	v_rcp_f32_e32 v62, v62
	v_rcp_f32_e32 v63, v63
	v_rcp_f32_e32 v64, v64
	v_rcp_f32_e32 v65, v65
	v_rcp_f32_e32 v58, v58
	v_rcp_f32_e32 v59, v59
	v_rcp_f32_e32 v60, v60
	v_rcp_f32_e32 v61, v61
	v_pk_mul_f32 v[34:35], v[34:35], v[38:39] op_sel_hi:[1,0]
	v_pk_mul_f32 v[40:41], v[80:81], v[38:39] op_sel_hi:[1,0]
	v_pk_mul_f32 v[36:37], v[36:37], v[38:39] op_sel_hi:[1,0]
	v_pk_mul_f32 v[38:39], v[66:67], v[38:39] op_sel_hi:[1,0]
	s_waitcnt vmcnt(16)
	v_lshlrev_b32_e32 v68, 16, v26
	v_and_b32_e32 v69, 0xffff0000, v26
	s_waitcnt vmcnt(15)
	v_lshlrev_b32_e32 v26, 16, v30
	v_lshlrev_b32_e32 v66, 16, v31
	v_and_b32_e32 v67, 0xffff0000, v31
	s_waitcnt vmcnt(7)
	v_pk_mul_f32 v[36:37], v[88:89], v[36:37]
	v_pk_mul_f32 v[38:39], v[38:39], v[90:91]
	s_waitcnt vmcnt(6)
	v_pk_mul_f32 v[34:35], v[76:77], v[34:35]
	v_pk_mul_f32 v[40:41], v[78:79], v[40:41]
	v_pk_mul_f32 v[36:37], v[62:63], v[36:37]
	v_pk_mul_f32 v[38:39], v[64:65], v[38:39]
	v_pk_mul_f32 v[34:35], v[58:59], v[34:35]
	v_pk_mul_f32 v[40:41], v[60:61], v[40:41]
	v_cvt_pk_bf16_f32 v36, v36, v37
	v_cvt_pk_bf16_f32 v37, v38, v39
	v_lshlrev_b64 v[38:39], 12, v[56:57]
	v_cvt_pk_bf16_f32 v34, v34, v35
	v_cvt_pk_bf16_f32 v35, v40, v41
	v_lshl_add_u64 v[38:39], v[46:47], 0, v[38:39]
	global_store_dwordx4 v[38:39], v[34:37], off
	v_lshlrev_b32_e32 v38, 16, v44
	v_and_b32_e32 v39, 0xffff0000, v44
	v_lshlrev_b32_e32 v34, 16, v42
	v_mul_f32_e32 v34, 0xbfb8aa3b, v34
	v_exp_f32_e32 v34, v34
	v_and_b32_e32 v35, 0xffff0000, v42
	v_lshlrev_b32_e32 v36, 16, v43
	v_and_b32_e32 v37, 0xffff0000, v43
	v_add_f32_e32 v34, 1.0, v34
	v_rcp_f32_e32 v40, v34
	v_mul_f32_e32 v34, 0xbfb8aa3b, v35
	v_exp_f32_e32 v34, v34
	v_lshlrev_b32_e32 v56, 16, v45
	v_and_b32_e32 v57, 0xffff0000, v45
	v_and_b32_e32 v35, 0xffff0000, v29
	v_add_f32_e32 v34, 1.0, v34
	v_rcp_f32_e32 v41, v34
	v_mul_f32_e32 v34, 0xbfb8aa3b, v36
	v_exp_f32_e32 v34, v34
	v_lshlrev_b32_e32 v36, 16, v33
	v_lshlrev_b32_e32 v64, 16, v27
	v_and_b32_e32 v65, 0xffff0000, v27
	v_add_f32_e32 v34, 1.0, v34
	v_rcp_f32_e32 v42, v34
	v_mul_f32_e32 v34, 0xbfb8aa3b, v37
	v_exp_f32_e32 v34, v34
	v_and_b32_e32 v37, 0xffff0000, v33
	v_and_b32_e32 v27, 0xffff0000, v30
	v_pk_add_f32 v[26:27], v[68:69], v[26:27]
	v_add_f32_e32 v34, 1.0, v34
	v_rcp_f32_e32 v43, v34
	v_mul_f32_e32 v34, 0xbfb8aa3b, v38
	v_exp_f32_e32 v34, v34
	v_pk_add_f32 v[64:65], v[64:65], v[66:67]
	v_pk_mul_f32 v[30:31], v[26:27], v[26:27]
	v_pk_mul_f32 v[66:67], v[64:65], v[64:65]
	v_add_f32_e32 v34, 1.0, v34
	v_rcp_f32_e32 v44, v34
	v_mul_f32_e32 v34, 0xbfb8aa3b, v39
	v_exp_f32_e32 v34, v34
	v_add_f32_e32 v30, v30, v31
	v_add_f32_e32 v30, v66, v30
	v_add_f32_e32 v30, v67, v30
	v_add_f32_e32 v34, 1.0, v34
	v_rcp_f32_e32 v45, v34
	v_mul_f32_e32 v34, 0xbfb8aa3b, v56
	v_exp_f32_e32 v34, v34
	s_nop 0
	v_add_f32_e32 v34, 1.0, v34
	v_rcp_f32_e32 v56, v34
	v_mul_f32_e32 v34, 0xbfb8aa3b, v57
	v_exp_f32_e32 v34, v34
	s_nop 0
	v_add_f32_e32 v34, 1.0, v34
	v_rcp_f32_e32 v57, v34
	v_lshlrev_b32_e32 v34, 16, v29
	v_pk_add_f32 v[58:59], v[34:35], v[36:37]
	v_lshlrev_b32_e32 v34, 16, v28
	v_and_b32_e32 v35, 0xffff0000, v28
	v_lshlrev_b32_e32 v28, 16, v32
	v_and_b32_e32 v29, 0xffff0000, v32
	v_pk_add_f32 v[28:29], v[34:35], v[28:29]
	s_nop 0
	s_nop 0
	v_pk_mul_f32 v[62:63], v[28:29], v[28:29]
	v_pk_mul_f32 v[60:61], v[58:59], v[58:59]
	v_add_f32_e32 v30, v62, v30
	v_add_f32_e32 v30, v63, v30
	v_add_f32_e32 v30, v60, v30
	v_add_f32_e32 v30, v61, v30
	s_nop 1
	v_add_f32_dpp v30, v30, v30 quad_perm:[1,0,3,2] row_mask:0xf bank_mask:0xf bound_ctrl:1
	s_nop 1
	v_add_f32_dpp v30, v30, v30 quad_perm:[2,3,0,1] row_mask:0xf bank_mask:0xf bound_ctrl:1
	s_nop 1
	v_add_f32_dpp v30, v30, v30 row_half_mirror row_mask:0xf bank_mask:0xf bound_ctrl:1
	s_nop 1
	v_add_f32_dpp v30, v30, v30 row_mirror row_mask:0xf bank_mask:0xf bound_ctrl:1
	v_fmamk_f32 v30, v30, 0x3c000000, v233
	v_rsq_f32_e32 v30, v30
	s_nop 0
	v_pk_mul_f32 v[26:27], v[26:27], v[30:31] op_sel_hi:[1,0]
	v_pk_mul_f32 v[28:29], v[28:29], v[30:31] op_sel_hi:[1,0]
	s_waitcnt vmcnt(5)
	v_pk_mul_f32 v[26:27], v[132:133], v[26:27]
	v_pk_mul_f32 v[36:37], v[64:65], v[30:31] op_sel_hi:[1, 0]
	v_pk_mul_f32 v[30:31], v[58:59], v[30:31] op_sel_hi:[1,0]
	v_pk_mul_f32 v[28:29], v[92:93], v[28:29]
	v_pk_mul_f32 v[30:31], v[30:31], v[94:95]
	v_pk_mul_f32 v[36:37], v[134:135], v[36:37]
	v_pk_mul_f32 v[28:29], v[44:45], v[28:29]
	v_pk_mul_f32 v[30:31], v[56:57], v[30:31]
	v_pk_mul_f32 v[26:27], v[40:41], v[26:27]
	v_pk_mul_f32 v[36:37], v[42:43], v[36:37]
	v_cvt_pk_bf16_f32 v28, v28, v29
	v_cvt_pk_bf16_f32 v29, v30, v31
	v_lshlrev_b64 v[30:31], 12, v[54:55]
	v_cvt_pk_bf16_f32 v26, v26, v27
	v_cvt_pk_bf16_f32 v27, v36, v37
	v_lshl_add_u64 v[30:31], v[46:47], 0, v[30:31]
	global_store_dwordx4 v[30:31], v[26:29], off
	v_lshlrev_b32_e32 v32, 16, v24
	v_and_b32_e32 v24, 0xffff0000, v24
	v_lshlrev_b32_e32 v26, 16, v22
	v_and_b32_e32 v22, 0xffff0000, v22
	v_mul_f32_e32 v22, 0xbfb8aa3b, v22
	v_exp_f32_e32 v22, v22
	v_lshlrev_b32_e32 v27, 16, v23
	v_and_b32_e32 v23, 0xffff0000, v23
	v_lshlrev_b32_e32 v34, 16, v25
	v_add_f32_e32 v22, 1.0, v22
	v_rcp_f32_e32 v29, v22
	v_mul_f32_e32 v22, 0xbfb8aa3b, v27
	v_exp_f32_e32 v22, v22
	v_and_b32_e32 v25, 0xffff0000, v25
	v_mul_f32_e32 v26, 0xbfb8aa3b, v26
	v_exp_f32_e32 v26, v26
	v_add_f32_e32 v22, 1.0, v22
	v_rcp_f32_e32 v30, v22
	v_mul_f32_e32 v22, 0xbfb8aa3b, v23
	v_exp_f32_e32 v22, v22
	v_and_b32_e32 v23, 0xffff0000, v17
	v_add_f32_e32 v26, 1.0, v26
	v_rcp_f32_e32 v28, v26
	v_add_f32_e32 v22, 1.0, v22
	v_rcp_f32_e32 v31, v22
	v_mul_f32_e32 v22, 0xbfb8aa3b, v32
	v_exp_f32_e32 v22, v22
	v_lshlrev_b32_e32 v42, 16, v15
	v_and_b32_e32 v43, 0xffff0000, v15
	v_lshlrev_b32_e32 v54, 16, v14
	v_add_f32_e32 v22, 1.0, v22
	v_rcp_f32_e32 v32, v22
	v_mul_f32_e32 v22, 0xbfb8aa3b, v24
	v_exp_f32_e32 v22, v22
	v_lshlrev_b32_e32 v24, 16, v21
	v_and_b32_e32 v55, 0xffff0000, v14
	v_lshlrev_b32_e32 v14, 16, v18
	v_add_f32_e32 v22, 1.0, v22
	v_rcp_f32_e32 v33, v22
	v_mul_f32_e32 v22, 0xbfb8aa3b, v34
	v_exp_f32_e32 v22, v22
	v_and_b32_e32 v15, 0xffff0000, v18
	v_lshlrev_b32_e32 v44, 16, v19
	v_and_b32_e32 v45, 0xffff0000, v19
	v_add_f32_e32 v22, 1.0, v22
	v_rcp_f32_e32 v34, v22
	v_mul_f32_e32 v22, 0xbfb8aa3b, v25
	v_exp_f32_e32 v22, v22
	v_and_b32_e32 v25, 0xffff0000, v21
	v_pk_add_f32 v[14:15], v[54:55], v[14:15]
	v_pk_add_f32 v[42:43], v[42:43], v[44:45]
	v_add_f32_e32 v22, 1.0, v22
	v_rcp_f32_e32 v35, v22
	v_lshlrev_b32_e32 v22, 16, v17
	v_pk_add_f32 v[36:37], v[22:23], v[24:25]
	v_lshlrev_b32_e32 v22, 16, v16
	v_and_b32_e32 v23, 0xffff0000, v16
	v_lshlrev_b32_e32 v16, 16, v20
	v_and_b32_e32 v17, 0xffff0000, v20
	v_pk_add_f32 v[16:17], v[22:23], v[16:17]
	s_nop 0
	s_nop 0
	v_pk_mul_f32 v[18:19], v[14:15], v[14:15]
	v_pk_mul_f32 v[44:45], v[42:43], v[42:43]
	v_add_f32_e32 v18, v18, v19
	v_add_f32_e32 v18, v44, v18
	v_pk_mul_f32 v[40:41], v[16:17], v[16:17]
	v_add_f32_e32 v18, v45, v18
	v_add_f32_e32 v18, v40, v18
	v_pk_mul_f32 v[38:39], v[36:37], v[36:37]
	v_add_f32_e32 v18, v41, v18
	v_add_f32_e32 v18, v38, v18
	v_add_f32_e32 v18, v39, v18
	s_nop 1
	v_add_f32_dpp v18, v18, v18 quad_perm:[1,0,3,2] row_mask:0xf bank_mask:0xf bound_ctrl:1
	s_nop 1
	v_add_f32_dpp v18, v18, v18 quad_perm:[2,3,0,1] row_mask:0xf bank_mask:0xf bound_ctrl:1
	s_nop 1
	v_add_f32_dpp v18, v18, v18 row_half_mirror row_mask:0xf bank_mask:0xf bound_ctrl:1
	s_nop 1
	v_add_f32_dpp v18, v18, v18 row_mirror row_mask:0xf bank_mask:0xf bound_ctrl:1
	v_fmamk_f32 v18, v18, 0x3c000000, v233
	v_rsq_f32_e32 v18, v18
	s_nop 0
	v_pk_mul_f32 v[14:15], v[14:15], v[18:19] op_sel_hi:[1,0]
	v_pk_mul_f32 v[16:17], v[16:17], v[18:19] op_sel_hi:[1,0]
	s_waitcnt vmcnt(4)
	v_pk_mul_f32 v[14:15], v[140:141], v[14:15]
	v_pk_mul_f32 v[24:25], v[42:43], v[18:19] op_sel_hi:[1, 0]
	v_pk_mul_f32 v[18:19], v[36:37], v[18:19] op_sel_hi:[1,0]
	v_pk_mul_f32 v[16:17], v[136:137], v[16:17]
	v_pk_mul_f32 v[18:19], v[18:19], v[138:139]
	v_pk_mul_f32 v[24:25], v[142:143], v[24:25]
	v_pk_mul_f32 v[16:17], v[32:33], v[16:17]
	v_pk_mul_f32 v[18:19], v[34:35], v[18:19]
	v_pk_mul_f32 v[14:15], v[28:29], v[14:15]
	v_pk_mul_f32 v[24:25], v[30:31], v[24:25]
	v_cvt_pk_bf16_f32 v16, v16, v17
	v_cvt_pk_bf16_f32 v17, v18, v19
	v_lshlrev_b64 v[18:19], 12, v[52:53]
	v_cvt_pk_bf16_f32 v14, v14, v15
	v_cvt_pk_bf16_f32 v15, v24, v25
	v_lshl_add_u64 v[18:19], v[46:47], 0, v[18:19]
	global_store_dwordx4 v[18:19], v[14:17], off
	v_lshlrev_b32_e32 v20, 16, v12
	v_and_b32_e32 v12, 0xffff0000, v12
	v_lshlrev_b32_e32 v14, 16, v10
	v_and_b32_e32 v10, 0xffff0000, v10
	v_mul_f32_e32 v10, 0xbfb8aa3b, v10
	v_exp_f32_e32 v10, v10
	v_lshlrev_b32_e32 v15, 16, v11
	v_and_b32_e32 v11, 0xffff0000, v11
	v_lshlrev_b32_e32 v22, 16, v13
	v_add_f32_e32 v10, 1.0, v10
	v_rcp_f32_e32 v17, v10
	v_mul_f32_e32 v10, 0xbfb8aa3b, v15
	v_exp_f32_e32 v10, v10
	v_and_b32_e32 v13, 0xffff0000, v13
	v_mul_f32_e32 v14, 0xbfb8aa3b, v14
	v_exp_f32_e32 v14, v14
	v_add_f32_e32 v10, 1.0, v10
	v_rcp_f32_e32 v18, v10
	v_mul_f32_e32 v10, 0xbfb8aa3b, v11
	v_exp_f32_e32 v10, v10
	v_and_b32_e32 v11, 0xffff0000, v5
	v_add_f32_e32 v14, 1.0, v14
	v_rcp_f32_e32 v16, v14
	v_add_f32_e32 v10, 1.0, v10
	v_rcp_f32_e32 v19, v10
	v_mul_f32_e32 v10, 0xbfb8aa3b, v20
	v_exp_f32_e32 v10, v10
	v_lshlrev_b32_e32 v30, 16, v3
	v_and_b32_e32 v31, 0xffff0000, v3
	v_lshlrev_b32_e32 v34, 16, v2
	v_add_f32_e32 v10, 1.0, v10
	v_rcp_f32_e32 v20, v10
	v_mul_f32_e32 v10, 0xbfb8aa3b, v12
	v_exp_f32_e32 v10, v10
	v_lshlrev_b32_e32 v12, 16, v9
	v_and_b32_e32 v35, 0xffff0000, v2
	v_lshlrev_b32_e32 v2, 16, v6
	v_add_f32_e32 v10, 1.0, v10
	v_rcp_f32_e32 v21, v10
	v_mul_f32_e32 v10, 0xbfb8aa3b, v22
	v_exp_f32_e32 v10, v10
	v_and_b32_e32 v3, 0xffff0000, v6
	v_lshlrev_b32_e32 v32, 16, v7
	v_and_b32_e32 v33, 0xffff0000, v7
	v_add_f32_e32 v10, 1.0, v10
	v_rcp_f32_e32 v22, v10
	v_mul_f32_e32 v10, 0xbfb8aa3b, v13
	v_exp_f32_e32 v10, v10
	v_and_b32_e32 v13, 0xffff0000, v9
	v_pk_add_f32 v[2:3], v[34:35], v[2:3]
	v_pk_add_f32 v[30:31], v[30:31], v[32:33]
	v_add_f32_e32 v10, 1.0, v10
	v_rcp_f32_e32 v23, v10
	v_lshlrev_b32_e32 v10, 16, v5
	v_pk_add_f32 v[24:25], v[10:11], v[12:13]
	v_lshlrev_b32_e32 v10, 16, v4
	v_and_b32_e32 v11, 0xffff0000, v4
	v_lshlrev_b32_e32 v4, 16, v8
	v_and_b32_e32 v5, 0xffff0000, v8
	v_pk_add_f32 v[4:5], v[10:11], v[4:5]
	s_nop 0
	s_nop 0
	v_pk_mul_f32 v[6:7], v[2:3], v[2:3]
	v_pk_mul_f32 v[32:33], v[30:31], v[30:31]
	v_add_f32_e32 v6, v6, v7
	v_add_f32_e32 v6, v32, v6
	v_pk_mul_f32 v[28:29], v[4:5], v[4:5]
	v_add_f32_e32 v6, v33, v6
	v_add_f32_e32 v6, v28, v6
	v_pk_mul_f32 v[26:27], v[24:25], v[24:25]
	v_add_f32_e32 v6, v29, v6
	v_add_f32_e32 v6, v26, v6
	v_add_f32_e32 v6, v27, v6
	s_nop 1
	v_add_f32_dpp v6, v6, v6 quad_perm:[1,0,3,2] row_mask:0xf bank_mask:0xf bound_ctrl:1
	s_nop 1
	v_add_f32_dpp v6, v6, v6 quad_perm:[2,3,0,1] row_mask:0xf bank_mask:0xf bound_ctrl:1
	s_nop 1
	v_add_f32_dpp v6, v6, v6 row_half_mirror row_mask:0xf bank_mask:0xf bound_ctrl:1
	s_nop 1
	v_add_f32_dpp v6, v6, v6 row_mirror row_mask:0xf bank_mask:0xf bound_ctrl:1
	v_fmamk_f32 v6, v6, 0x3c000000, v233
	v_rsq_f32_e32 v6, v6
	s_nop 0
	v_pk_mul_f32 v[2:3], v[2:3], v[6:7] op_sel_hi:[1,0]
	v_pk_mul_f32 v[4:5], v[4:5], v[6:7] op_sel_hi:[1,0]
	s_waitcnt vmcnt(3)
	v_pk_mul_f32 v[2:3], v[148:149], v[2:3]
	v_pk_mul_f32 v[12:13], v[30:31], v[6:7] op_sel_hi:[1, 0]
	v_pk_mul_f32 v[6:7], v[24:25], v[6:7] op_sel_hi:[1,0]
	v_pk_mul_f32 v[4:5], v[144:145], v[4:5]
	v_pk_mul_f32 v[6:7], v[6:7], v[146:147]
	v_pk_mul_f32 v[12:13], v[150:151], v[12:13]
	v_pk_mul_f32 v[4:5], v[20:21], v[4:5]
	v_pk_mul_f32 v[6:7], v[22:23], v[6:7]
	v_pk_mul_f32 v[2:3], v[16:17], v[2:3]
	v_pk_mul_f32 v[12:13], v[18:19], v[12:13]
	v_cvt_pk_bf16_f32 v4, v4, v5
	v_cvt_pk_bf16_f32 v5, v6, v7
	v_lshlrev_b64 v[6:7], 12, v[50:51]
	v_cvt_pk_bf16_f32 v2, v2, v3
	v_cvt_pk_bf16_f32 v3, v12, v13
	v_lshl_add_u64 v[6:7], v[46:47], 0, v[6:7]
	global_store_dwordx4 v[6:7], v[2:5], off
	v_mov_b32_e32 v11, v147
	v_mov_b32_e32 v72, v88
	v_mov_b32_e32 v73, v89
	v_mov_b32_e32 v74, v90
	v_mov_b32_e32 v75, v91
	s_waitcnt vmcnt(1)
	s_cbranch_vccnz .LBB0_463
	s_branch .LBB0_403
